# GEMM first-unit prologue: K-tile 1 loads issued together with K-tile 0 (before the first wait/barrier) in all five GEMM prologues
# baseline (speedup 1.0000x reference)
.LBB0_460:
	s_add_u32 s10, s4, 0xae00000
	s_addc_u32 s11, s5, 0
	s_add_u32 s14, s4, 0x600000
	s_addc_u32 s15, s5, 0
	s_mul_i32 s13, s74, 0x18c00
	s_mul_hi_u32 s1, s74, 0x18c00
	s_add_u32 s13, s4, s13
	s_addc_u32 s1, s5, s1
	s_add_u32 s53, s13, 0x300000
	s_addc_u32 s79, s1, 0
	s_add_u32 s16, s4, 0x500000
	s_addc_u32 s17, s5, 0
	s_add_u32 s18, s4, 0x580000
	s_addc_u32 s19, s5, 0
	s_lshl_b32 s4, s22, 5
	s_and_b32 s61, s4, 0x60
	s_add_i32 m0, s90, 0x18000
	v_lshl_add_u64 v[6:7], v[6:7], 0, s[30:31]
	s_lshl_b32 s60, s21, 6
	s_lshl_b32 s1, s21, 13
	s_lshl_b32 s13, s61, 7
	global_load_lds_dwordx4 v[6:7], off
	v_lshl_add_u64 v[4:5], v[4:5], 0, s[30:31]
	s_add_i32 m0, s90, 0x1a000
	s_add_i32 s88, s90, 0x8000
	s_add_i32 s89, s90, 0xa000
	global_load_lds_dwordx4 v[4:5], off
	v_lshl_add_u64 v[0:1], v[0:1], 0, s[30:31]
	s_mov_b32 m0, s88
	s_add_u32 s4, s6, 0x40080
	global_load_lds_dwordx4 v[0:1], off
	v_lshl_add_u64 v[0:1], v[2:3], 0, s[30:31]
	s_mov_b32 m0, s89
	s_addc_u32 s5, s7, 0
	global_load_lds_dwordx4 v[0:1], off
	s_add_i32 m0, s90, 0x1c000
	v_lshl_add_u64 v[0:1], s[4:5], 0, v[148:149]
	global_load_lds_dwordx4 v[0:1], off
	v_lshl_add_u64 v[0:1], s[4:5], 0, v[152:153]
	s_add_i32 m0, s90, 0x1e000
	v_bfe_u32 v177, v8, 4, 2
	global_load_lds_dwordx4 v[0:1], off
	s_waitcnt vmcnt(8)
	s_barrier
	v_and_b32_e32 v176, 15, v8
	v_lshlrev_b32_e32 v0, 4, v177
	v_lshlrev_b32_e32 v1, 2, v8
	v_lshl_or_b32 v0, v176, 6, v0
	v_and_b32_e32 v1, 32, v1
	v_bitop3_b32 v2, v0, s1, v1 bitop3:0xde
	v_bitop3_b32 v178, v0, s13, v1 bitop3:0xde
	v_lshlrev_b32_e32 v0, 14, v12
	v_and_b32_e32 v0, 0xffff8000, v0
	v_lshl_add_u32 v0, v13, 11, v0
	v_and_b32_e32 v1, 1, v12
	v_lshl_or_b32 v0, v1, 6, v0
	v_lshl_add_u32 v154, v14, 1, v0
	v_lshlrev_b32_e32 v0, 14, v9
	v_and_b32_e32 v0, 0xffff8000, v0
	s_waitcnt vmcnt(6)
	v_lshl_add_u32 v0, v10, 11, v0
	v_and_b32_e32 v1, 1, v9
	s_cmpk_lt_u32 s20, 0x100
	v_lshl_or_b32 v0, v1, 6, v0
	s_cselect_b64 s[20:21], -1, 0
	v_mov_b32_e32 v155, v65
	v_lshl_add_u32 v156, v11, 1, v0
	v_mov_b32_e32 v157, v65
	s_mov_b32 s63, 0
	v_add_u32_e32 v179, 0, v2
	s_barrier
	s_branch .LBB0_463

.LBB0_1825:
	v_bfe_u32 v147, v8, 4, 2
	s_lshl_b32 s24, s24, 5
	v_and_b32_e32 v146, 15, v8
	s_lshl_b32 s17, s22, 6
	v_lshlrev_b32_e32 v11, 4, v147
	v_lshlrev_b32_e32 v8, 2, v8
	s_lshl_b32 s25, s22, 13
	s_and_b32 s22, s24, 0x60
	v_lshl_or_b32 v11, v146, 6, v11
	v_and_b32_e32 v8, 32, v8
	s_lshl_b32 s24, s22, 7
	v_bitop3_b32 v58, v11, s24, v8 bitop3:0xde
	s_add_u32 s24, s14, 0xc00080
	v_mov_b32_e32 v45, v65
	v_bitop3_b32 v8, v11, s25, v8 bitop3:0xde
	s_addc_u32 s25, s15, 0
	v_mov_b32_e32 v49, v65
	s_add_i32 m0, s19, 0x18000
	v_lshl_add_u64 v[12:13], s[24:25], 0, v[44:45]
	global_load_lds_dwordx4 v[12:13], off
	v_lshl_add_u64 v[12:13], s[24:25], 0, v[48:49]
	s_add_i32 m0, s19, 0x1a000
	s_add_i32 s24, s19, 0x8000
	s_add_i32 s25, s19, 0xa000
	global_load_lds_dwordx4 v[12:13], off
	v_lshl_add_u64 v[2:3], v[2:3], 0, s[30:31]
	s_mov_b32 m0, s24
	s_add_u32 s14, s14, 0xc40080
	global_load_lds_dwordx4 v[2:3], off
	v_lshl_add_u64 v[0:1], v[0:1], 0, s[30:31]
	s_mov_b32 m0, s25
	s_addc_u32 s15, s15, 0
	global_load_lds_dwordx4 v[0:1], off
	s_add_i32 m0, s19, 0x1c000
	v_lshl_add_u64 v[0:1], s[14:15], 0, v[44:45]
	global_load_lds_dwordx4 v[0:1], off
	v_lshl_add_u64 v[0:1], s[14:15], 0, v[48:49]
	s_add_i32 m0, s19, 0x1e000
	s_add_u32 s13, s6, s13
	global_load_lds_dwordx4 v[0:1], off
	s_waitcnt vmcnt(8)
	s_barrier
	s_addc_u32 s12, s7, s12
	s_add_u32 s33, s13, 0xc00100
	s_addc_u32 s34, s12, 0
	v_lshlrev_b32_e32 v0, 14, v7
	v_and_b32_e32 v0, 0xffff8000, v0
	s_add_u32 s35, s6, s10
	v_lshl_add_u32 v0, v9, 11, v0
	v_and_b32_e32 v1, 1, v7
	s_addc_u32 s44, s7, s11
	v_lshl_or_b32 v0, v1, 6, v0
	s_add_u32 s10, s35, 0x9640080
	v_lshl_add_u32 v0, v10, 1, v0
	v_mov_b32_e32 v1, v65
	s_addc_u32 s11, s44, 0
	v_lshl_add_u64 v[50:51], s[10:11], 0, v[0:1]
	v_lshlrev_b32_e32 v0, 14, v4
	v_and_b32_e32 v0, 0xffff8000, v0
	v_lshl_add_u32 v0, v5, 11, v0
	v_and_b32_e32 v1, 1, v4
	v_lshl_or_b32 v0, v1, 6, v0
	s_waitcnt vmcnt(6)
	v_lshl_add_u32 v0, v6, 1, v0
	v_mov_b32_e32 v1, v65
	v_lshl_add_u64 v[56:57], s[10:11], 0, v[0:1]
	v_mov_b32_e32 v0, 0
	s_mov_b32 s53, -2
	s_mov_b64 s[10:11], 0
	v_add_u32_e32 v59, 0, v8
	v_mov_b32_e32 v1, v0
	v_mov_b32_e32 v2, v0
	v_mov_b32_e32 v3, v0
	v_mov_b32_e32 v4, v0
	v_mov_b32_e32 v5, v0
	v_mov_b32_e32 v6, v0
	v_mov_b32_e32 v7, v0
	v_mov_b32_e32 v16, v0
	v_mov_b32_e32 v17, v0
	v_mov_b32_e32 v18, v0
	v_mov_b32_e32 v19, v0
	v_mov_b32_e32 v20, v0
	v_mov_b32_e32 v21, v0
	v_mov_b32_e32 v22, v0
	v_mov_b32_e32 v23, v0
	v_mov_b32_e32 v32, v0
	v_mov_b32_e32 v33, v0
	v_mov_b32_e32 v34, v0
	v_mov_b32_e32 v35, v0
	v_mov_b32_e32 v36, v0
	v_mov_b32_e32 v37, v0
	v_mov_b32_e32 v38, v0
	v_mov_b32_e32 v39, v0
	v_mov_b32_e32 v66, v0
	v_mov_b32_e32 v67, v0
	v_mov_b32_e32 v68, v0
	v_mov_b32_e32 v69, v0
	v_mov_b32_e32 v70, v0
	v_mov_b32_e32 v71, v0
	v_mov_b32_e32 v72, v0
	v_mov_b32_e32 v73, v0
	v_mov_b32_e32 v8, v0
	v_mov_b32_e32 v9, v0
	v_mov_b32_e32 v10, v0
	v_mov_b32_e32 v11, v0
	v_mov_b32_e32 v12, v0
	v_mov_b32_e32 v13, v0
	v_mov_b32_e32 v14, v0
	v_mov_b32_e32 v15, v0
	v_mov_b32_e32 v24, v0
	v_mov_b32_e32 v25, v0
	v_mov_b32_e32 v26, v0
	v_mov_b32_e32 v27, v0
	v_mov_b32_e32 v28, v0
	v_mov_b32_e32 v29, v0
	v_mov_b32_e32 v30, v0
	v_mov_b32_e32 v31, v0
	v_mov_b32_e32 v40, v0
	v_mov_b32_e32 v41, v0
	v_mov_b32_e32 v42, v0
	v_mov_b32_e32 v43, v0
	v_mov_b32_e32 v52, v0
	v_mov_b32_e32 v53, v0
	v_mov_b32_e32 v54, v0
	v_mov_b32_e32 v55, v0
	v_mov_b32_e32 v74, v0
	v_mov_b32_e32 v75, v0
	v_mov_b32_e32 v76, v0
	v_mov_b32_e32 v77, v0
	v_mov_b32_e32 v78, v0
	v_mov_b32_e32 v79, v0
	v_mov_b32_e32 v80, v0
	v_mov_b32_e32 v81, v0
	v_mov_b32_e32 v82, v0
	v_mov_b32_e32 v83, v0
	v_mov_b32_e32 v84, v0
	v_mov_b32_e32 v85, v0
	v_mov_b32_e32 v86, v0
	v_mov_b32_e32 v87, v0
	v_mov_b32_e32 v88, v0
	v_mov_b32_e32 v89, v0
	v_mov_b32_e32 v98, v0
	v_mov_b32_e32 v99, v0
	v_mov_b32_e32 v100, v0
	v_mov_b32_e32 v101, v0
	v_mov_b32_e32 v102, v0
	v_mov_b32_e32 v103, v0
	v_mov_b32_e32 v104, v0
	v_mov_b32_e32 v105, v0
	v_mov_b32_e32 v114, v0
	v_mov_b32_e32 v115, v0
	v_mov_b32_e32 v116, v0
	v_mov_b32_e32 v117, v0
	v_mov_b32_e32 v118, v0
	v_mov_b32_e32 v119, v0
	v_mov_b32_e32 v120, v0
	v_mov_b32_e32 v121, v0
	v_mov_b32_e32 v130, v0
	v_mov_b32_e32 v131, v0
	v_mov_b32_e32 v132, v0
	v_mov_b32_e32 v133, v0
	v_mov_b32_e32 v134, v0
	v_mov_b32_e32 v135, v0
	v_mov_b32_e32 v136, v0
	v_mov_b32_e32 v137, v0
	v_mov_b32_e32 v90, v0
	v_mov_b32_e32 v91, v0
	v_mov_b32_e32 v92, v0
	v_mov_b32_e32 v93, v0
	v_mov_b32_e32 v94, v0
	v_mov_b32_e32 v95, v0
	v_mov_b32_e32 v96, v0
	v_mov_b32_e32 v97, v0
	v_mov_b32_e32 v106, v0
	v_mov_b32_e32 v107, v0
	v_mov_b32_e32 v108, v0
	v_mov_b32_e32 v109, v0
	v_mov_b32_e32 v110, v0
	v_mov_b32_e32 v111, v0
	v_mov_b32_e32 v112, v0
	v_mov_b32_e32 v113, v0
	v_mov_b32_e32 v122, v0
	v_mov_b32_e32 v123, v0
	v_mov_b32_e32 v124, v0
	v_mov_b32_e32 v125, v0
	v_mov_b32_e32 v126, v0
	v_mov_b32_e32 v127, v0
	v_mov_b32_e32 v128, v0
	v_mov_b32_e32 v129, v0
	v_mov_b32_e32 v138, v0
	v_mov_b32_e32 v139, v0
	v_mov_b32_e32 v140, v0
	v_mov_b32_e32 v141, v0
	v_mov_b32_e32 v142, v0
	v_mov_b32_e32 v143, v0
	v_mov_b32_e32 v144, v0
	v_mov_b32_e32 v145, v0
	s_barrier

.LBB0_1878:
	s_add_u32 s12, s6, 0x6600000
	s_addc_u32 s13, s7, 0
	s_add_u32 s14, s6, 0x9600000
	s_addc_u32 s15, s7, 0
	v_readlane_b32 s0, v255, 30
	s_add_u32 s16, s6, 0x600000
	v_readlane_b32 s1, v255, 31
	s_addc_u32 s17, s7, 0
	s_lshl_b64 s[18:19], s[0:1], 2
	s_add_u32 s0, s6, s18
	s_addc_u32 s1, s7, s19
	s_add_u32 s79, s0, 0x102000
	s_addc_u32 s84, s1, 0
	v_readlane_b32 s0, v255, 32
	v_readlane_b32 s1, v255, 33
	s_lshl_b64 s[18:19], s[0:1], 2
	s_add_u32 s0, s6, s18
	s_addc_u32 s1, s7, s19
	v_bfe_u32 v191, v14, 4, 2
	s_add_u32 s18, s0, 0x209000
	v_and_b32_e32 v226, 15, v14
	v_lshlrev_b32_e32 v15, 4, v191
	v_lshlrev_b32_e32 v14, 2, v14
	s_addc_u32 s19, s1, 0
	s_and_b32 s85, s20, 3
	v_lshl_or_b32 v15, v226, 6, v15
	s_lshl_b32 s0, s9, 13
	v_and_b32_e32 v14, 32, v14
	s_add_i32 m0, s53, 0x18000
	v_lshl_add_u64 v[6:7], v[6:7], 0, s[30:31]
	s_lshl_b32 s86, s9, 6
	v_bitop3_b32 v16, v15, s0, v14 bitop3:0xde
	s_lshl_b32 s87, s85, 5
	s_lshl_b32 s0, s85, 12
	global_load_lds_dwordx4 v[6:7], off
	v_lshl_add_u64 v[4:5], v[4:5], 0, s[30:31]
	s_add_i32 m0, s53, 0x1a000
	s_add_i32 s88, s53, 0x8000
	s_add_i32 s89, s53, 0xa000
	global_load_lds_dwordx4 v[4:5], off
	v_lshl_add_u64 v[0:1], v[0:1], 0, s[30:31]
	s_mov_b32 m0, s88
	s_add_u32 s6, s34, 0x40080
	global_load_lds_dwordx4 v[0:1], off
	v_lshl_add_u64 v[0:1], v[2:3], 0, s[30:31]
	s_mov_b32 m0, s89
	s_addc_u32 s7, s35, 0
	global_load_lds_dwordx4 v[0:1], off
	s_add_i32 m0, s53, 0x1c000
	v_lshl_add_u64 v[0:1], s[6:7], 0, v[64:65]
	global_load_lds_dwordx4 v[0:1], off
	v_lshl_add_u64 v[0:1], s[6:7], 0, v[196:197]
	s_add_i32 m0, s53, 0x1e000
	v_bitop3_b32 v227, v15, s0, v14 bitop3:0xde
	global_load_lds_dwordx4 v[0:1], off
	s_waitcnt vmcnt(8)
	s_barrier
	v_lshlrev_b32_e32 v0, 14, v8
	v_and_b32_e32 v0, 0xffff8000, v0
	v_lshl_add_u32 v0, v9, 11, v0
	v_and_b32_e32 v1, 1, v8
	v_lshl_or_b32 v0, v1, 6, v0
	v_lshl_add_u32 v202, v10, 1, v0
	v_lshlrev_b32_e32 v0, 14, v12
	v_and_b32_e32 v0, 0xffff8000, v0
	s_waitcnt vmcnt(6)
	v_lshl_add_u32 v0, v11, 11, v0
	v_and_b32_e32 v1, 1, v12
	s_cmpk_lt_u32 s8, 0x100
	v_lshl_or_b32 v0, v1, 6, v0
	v_readlane_b32 s0, v255, 2
	s_cselect_b64 s[20:21], -1, 0
	v_mov_b32_e32 v203, v65
	v_lshl_add_u32 v204, v13, 1, v0
	v_mov_b32_e32 v205, v65
	s_mov_b32 s90, 0
	v_add_u32_e32 v240, 0, v16
	v_readlane_b32 s91, v254, 54
	s_mov_b32 s8, s0
	s_barrier
	v_readlane_b32 s1, v255, 3
	s_branch .LBB0_1881

.LBB0_2119:
	s_add_u32 s20, s6, 0x10800000
	s_addc_u32 s21, s7, 0
	s_add_u32 s22, s6, 0x600000
	s_addc_u32 s23, s7, 0
	s_mul_i32 s1, s74, 0x24000
	s_mul_hi_u32 s0, s74, 0x24000
	s_add_u32 s1, s6, s1
	s_addc_u32 s0, s7, s0
	v_bfe_u32 v161, v14, 4, 2
	s_add_u32 s88, s1, 0x400000
	v_and_b32_e32 v160, 15, v14
	v_lshlrev_b32_e32 v15, 4, v161
	v_lshlrev_b32_e32 v14, 2, v14
	s_addc_u32 s89, s0, 0
	v_lshl_or_b32 v15, v160, 6, v15
	s_lshl_b32 s0, s5, 13
	v_and_b32_e32 v14, 32, v14
	v_bitop3_b32 v16, v15, s0, v14 bitop3:0xde
	s_lshl_b32 s0, s4, 5
	s_and_b32 s91, s0, 0x60
	s_add_i32 m0, s61, 0x18000
	v_lshl_add_u64 v[6:7], v[6:7], 0, s[30:31]
	s_lshl_b32 s90, s5, 6
	s_lshl_b32 s0, s91, 7
	global_load_lds_dwordx4 v[6:7], off
	v_lshl_add_u64 v[4:5], v[4:5], 0, s[30:31]
	s_add_i32 m0, s61, 0x1a000
	s_add_i32 s4, s61, 0x8000
	s_add_i32 s5, s61, 0xa000
	v_bitop3_b32 v162, v15, s0, v14 bitop3:0xde
	global_load_lds_dwordx4 v[4:5], off
	v_lshl_add_u64 v[0:1], v[0:1], 0, s[30:31]
	s_mov_b32 m0, s4
	s_add_u32 s0, s34, 0x40080
	global_load_lds_dwordx4 v[0:1], off
	v_lshl_add_u64 v[0:1], v[2:3], 0, s[30:31]
	s_mov_b32 m0, s5
	s_addc_u32 s1, s35, 0
	global_load_lds_dwordx4 v[0:1], off
	s_add_i32 m0, s61, 0x1c000
	v_lshl_add_u64 v[0:1], s[0:1], 0, v[64:65]
	global_load_lds_dwordx4 v[0:1], off
	v_lshl_add_u64 v[0:1], s[0:1], 0, v[146:147]
	s_add_i32 m0, s61, 0x1e000
	s_cmpk_lt_u32 s8, 0x100
	global_load_lds_dwordx4 v[0:1], off
	s_waitcnt vmcnt(8)
	s_barrier
	v_lshlrev_b32_e32 v0, 14, v8
	v_and_b32_e32 v0, 0xffff8000, v0
	v_lshl_add_u32 v0, v9, 11, v0
	v_and_b32_e32 v1, 1, v8
	v_lshl_or_b32 v0, v1, 6, v0
	v_lshl_add_u32 v152, v10, 1, v0
	v_lshlrev_b32_e32 v0, 14, v12
	v_and_b32_e32 v0, 0xffff8000, v0
	s_waitcnt vmcnt(6)
	v_lshl_add_u32 v0, v11, 11, v0
	v_and_b32_e32 v1, 1, v12
	v_lshl_or_b32 v0, v1, 6, v0
	v_readlane_b32 s0, v254, 56
	s_cselect_b64 s[24:25], -1, 0
	v_mov_b32_e32 v153, v65
	v_lshl_add_u32 v154, v13, 1, v0
	v_mov_b32_e32 v155, v65
	s_mov_b32 s12, 0
	v_add_u32_e32 v163, 0, v16
	v_readlane_b32 s9, v254, 55
	s_mov_b32 s8, s0
	s_barrier
	v_readlane_b32 s1, v254, 57
	s_branch .LBB0_2122

.LBB0_2172:
	s_add_u32 s18, s24, 0x6600000
	s_addc_u32 s19, s25, 0
	s_add_u32 s20, s24, 0x9600000
	s_addc_u32 s21, s25, 0
	v_readlane_b32 s0, v255, 30
	s_add_u32 s22, s24, 0x600000
	v_readlane_b32 s1, v255, 31
	s_addc_u32 s23, s25, 0
	s_lshl_b64 s[0:1], s[0:1], 2
	s_add_u32 s0, s24, s0
	s_addc_u32 s1, s25, s1
	s_add_u32 s75, s0, 0x105000
	s_addc_u32 s79, s1, 0
	v_readlane_b32 s0, v255, 32
	v_readlane_b32 s1, v255, 33
	s_lshl_b64 s[0:1], s[0:1], 2
	s_add_u32 s0, s24, s0
	s_addc_u32 s1, s25, s1
	s_add_u32 s9, s0, 0x212000
	s_addc_u32 s12, s1, 0
	v_readlane_b32 s0, v255, 36
	v_readlane_b32 s1, v255, 37
	v_bfe_u32 v191, v14, 4, 2
	s_and_b64 s[0:1], s[0:1], exec
	v_and_b32_e32 v240, 15, v14
	v_lshlrev_b32_e32 v15, 4, v191
	v_lshlrev_b32_e32 v14, 2, v14
	s_cselect_b32 s1, 0, s12
	s_cselect_b32 s0, 0, s9
	s_and_b32 s83, s8, 3
	s_lshl_b32 s84, s5, 6
	v_lshl_or_b32 v15, v240, 6, v15
	s_lshl_b32 s5, s5, 13
	v_and_b32_e32 v14, 32, v14
	s_add_i32 m0, s61, 0x18000
	v_lshl_add_u64 v[6:7], v[6:7], 0, s[30:31]
	v_bitop3_b32 v16, v15, s5, v14 bitop3:0xde
	s_lshl_b32 s85, s83, 5
	s_lshl_b32 s5, s83, 12
	global_load_lds_dwordx4 v[6:7], off
	v_lshl_add_u64 v[4:5], v[4:5], 0, s[30:31]
	s_add_i32 m0, s61, 0x1a000
	s_add_i32 s86, s61, 0x8000
	s_add_i32 s87, s61, 0xa000
	global_load_lds_dwordx4 v[4:5], off
	v_lshl_add_u64 v[0:1], v[0:1], 0, s[30:31]
	s_mov_b32 m0, s86
	s_add_u32 s8, s6, 0x100080
	global_load_lds_dwordx4 v[0:1], off
	v_lshl_add_u64 v[0:1], v[2:3], 0, s[30:31]
	s_mov_b32 m0, s87
	s_addc_u32 s9, s7, 0
	global_load_lds_dwordx4 v[0:1], off
	s_add_i32 m0, s61, 0x1c000
	v_lshl_add_u64 v[0:1], s[8:9], 0, v[64:65]
	global_load_lds_dwordx4 v[0:1], off
	v_lshl_add_u64 v[0:1], s[8:9], 0, v[196:197]
	s_add_i32 m0, s61, 0x1e000
	v_bitop3_b32 v241, v15, s5, v14 bitop3:0xde
	global_load_lds_dwordx4 v[0:1], off
	s_waitcnt vmcnt(8)
	s_barrier
	v_lshlrev_b32_e32 v0, 16, v8
	v_and_b32_e32 v0, 0xfffe0000, v0
	v_lshl_add_u32 v0, v9, 13, v0
	v_and_b32_e32 v1, 1, v8
	v_lshl_or_b32 v0, v1, 6, v0
	v_lshl_add_u32 v202, v10, 1, v0
	v_lshlrev_b32_e32 v0, 16, v12
	v_and_b32_e32 v0, 0xfffe0000, v0
	s_waitcnt vmcnt(6)
	v_lshl_add_u32 v0, v11, 13, v0
	v_and_b32_e32 v1, 1, v12
	s_cmpk_lt_u32 s4, 0x100
	v_lshl_or_b32 v0, v1, 6, v0
	v_readlane_b32 s4, v255, 2
	s_mov_b32 s82, 0
	s_cselect_b64 s[12:13], -1, 0
	v_mov_b32_e32 v203, v65
	v_lshl_add_u32 v204, v13, 1, v0
	v_mov_b32_e32 v205, v65
	v_add_u32_e32 v242, 0, v16
	v_readlane_b32 s88, v254, 54
	s_mov_b32 s89, s4
	s_barrier
	v_readlane_b32 s5, v255, 3
	s_branch .LBB0_2175
